# prep_mlstm: gate scalar loads (i/f pre-activations and biases) requested at the top of the unit loop instead of two serial round trips in wave 0 while the other waves wait at the barrier
# baseline (speedup 1.0000x reference)
.LBB0_328:
	v_mov_b32_e32 v148, v164
	s_waitcnt vmcnt(63) expcnt(7) lgkmcnt(15)
	v_ashrrev_i32_e32 v112, 8, v148
	v_add_u32_e32 v176, s47, v112
	v_bfe_u32 v181, v176, 7, 3
	v_cmp_gt_i32_e32 vcc, s3, v148
	v_lshlrev_b32_e32 v177, 7, v181
	v_and_b32_e32 v224, 0x7f, v176
	v_lshrrev_b32_e32 v225, 10, v176
	v_lshlrev_b32_e32 v225, 13, v225
	v_lshl_or_b32 v224, v224, 6, v225
	v_and_b32_e32 v225, 63, v148
	v_add_u32_e32 v224, v224, v225
	v_lshlrev_b32_e32 v224, 2, v224
	v_lshl_add_u32 v224, v181, 16, v224
	v_readlane_b32 s98, v250, 27
	v_readlane_b32 s99, v250, 28
	v_add_u32_e32 v225, 0x480000, v224
	v_readlane_b32 s100, v250, 25
	v_readlane_b32 s101, v250, 26
	global_load_dword v226, v225, s[16:17]
	v_add_u32_e32 v225, 0x400000, v224
	global_load_dword v227, v225, s[16:17]
	v_lshlrev_b32_e32 v225, 2, v181
	s_nop 4
	global_load_dword v228, v225, s[98:99]
	global_load_dword v229, v225, s[100:101]
	s_barrier
	s_and_saveexec_b64 s[0:1], vcc
	v_readlane_b32 s48, v250, 19
	v_readlane_b32 s49, v250, 20
	v_readlane_b32 s50, v250, 21
	v_readlane_b32 s51, v250, 22
	v_readlane_b32 s52, v250, 23
	v_readlane_b32 s53, v250, 24
	v_readlane_b32 s54, v250, 25
	v_readlane_b32 s55, v250, 26
	v_readlane_b32 s56, v250, 27
	v_readlane_b32 s57, v250, 28
	v_readlane_b32 s58, v250, 29
	v_readlane_b32 s59, v250, 30
	v_readlane_b32 s60, v250, 31
	v_readlane_b32 s61, v250, 32
	v_readlane_b32 s62, v250, 33
	v_readlane_b32 s63, v250, 34
	s_cbranch_execz .LBB0_341
	v_max_i32_e32 v0, 0x200, v148
	v_sub_u32_e32 v0, v0, v148
	v_add_u32_e32 v0, 0x1ff, v0
	v_and_b32_e32 v6, 0x7f, v148
	v_cmp_lt_u32_e32 vcc, s30, v0
	s_mov_b64 s[6:7], -1
	v_mov_b32_e32 v4, v148
	s_and_saveexec_b64 s[4:5], vcc
	s_cbranch_execz .LBB0_338
	v_lshrrev_b32_e32 v7, 9, v0
	v_add_u32_e32 v0, -1, v7
	v_add_u32_e32 v149, 0x200, v148
	v_lshrrev_b32_e32 v1, 1, v0
	v_add_u32_e32 v8, 1, v1
	v_cmp_lt_u32_e32 vcc, 5, v0
	v_mov_b32_e32 v11, 0
	v_mov_b64_e32 v[0:1], v[148:149]
	s_and_saveexec_b64 s[6:7], vcc
	s_cbranch_execz .LBB0_334
	v_readlane_b32 s48, v250, 19
	v_and_b32_e32 v9, -4, v8
	v_lshl_add_u32 v10, v148, 2, 0
	s_mov_b32 s10, 0
	s_mov_b64 s[8:9], 0
	v_lshlrev_b32_e32 v2, 2, v177
	v_mov_b32_e32 v3, v145
	v_lshlrev_b32_e32 v4, 2, v6
	v_mov_b32_e32 v5, v145
	v_mov_b64_e32 v[0:1], v[148:149]
	v_readlane_b32 s52, v250, 23
	v_readlane_b32 s53, v250, 24
	v_readlane_b32 s49, v250, 20
	v_readlane_b32 s50, v250, 21
	v_readlane_b32 s51, v250, 22
	v_readlane_b32 s54, v250, 25
	v_readlane_b32 s55, v250, 26
	v_readlane_b32 s56, v250, 27
	v_readlane_b32 s57, v250, 28
	v_readlane_b32 s58, v250, 29
	v_readlane_b32 s59, v250, 30
	v_readlane_b32 s60, v250, 31
	v_readlane_b32 s61, v250, 32
	v_readlane_b32 s62, v250, 33
	v_readlane_b32 s63, v250, 34

.LBB0_341:
	s_or_b64 exec, exec, s[0:1]
	v_and_b32_e32 v113, 0x7f, v176
	v_ashrrev_i32_e32 v152, 10, v176
	v_sub_u32_e64 v0, v113, 1 clamp
	v_ashrrev_i32_e32 v153, 31, v152
	v_lshl_or_b32 v12, v152, 7, v0
	v_lshlrev_b64 v[154:155], 13, v[152:153]
	v_lshlrev_b32_e32 v182, 6, v113
	v_mad_i64_i32 v[96:97], s[0:1], v12, 3, 0
	v_bfe_u32 v156, v148, 4, 4
	v_or_b32_e32 v154, v154, v182
	v_cmp_gt_u32_sdwa s[0:1], v148, v161 src0_sel:BYTE_0 src1_sel:DWORD
	v_mov_b64_e32 v[4:5], 0x20600000
	v_mov_b64_e32 v[2:3], 0x5000
	v_add_u32_e32 v98, -3, v156
	v_mov_b32_e32 v6, v156
	v_mov_b64_e32 v[8:9], v[96:97]
	s_waitcnt lgkmcnt(0)
	s_barrier
	s_and_saveexec_b64 s[4:5], s[0:1]
	v_mov_b64_e32 v[4:5], 0x8100000
	v_mov_b64_e32 v[2:3], 0x6000
	v_mov_b32_e32 v6, v98
	v_mov_b64_e32 v[8:9], v[154:155]
	s_or_b64 exec, exec, s[4:5]
	v_lshlrev_b32_e32 v149, 3, v148
	v_and_b32_e32 v180, 0x78, v149
	v_or_b32_e32 v114, v177, v180
	v_lshl_or_b32 v144, v114, 1, v162
	v_lshl_add_u64 v[4:5], s[82:83], 0, v[4:5]
	v_mov_b32_e32 v7, v145
	v_lshl_add_u64 v[4:5], v[4:5], 0, v[144:145]
	v_lshl_add_u64 v[6:7], v[8:9], 0, v[6:7]
	v_mad_u64_u32 v[4:5], s[4:5], v6, v2, v[4:5]
	v_mov_b32_e32 v6, v5
	v_cmp_gt_u32_sdwa vcc, v148, v163 src0_sel:BYTE_0 src1_sel:DWORD
	v_mad_u64_u32 v[2:3], s[4:5], v7, v2, v[6:7]
	s_nop 0
	v_cndmask_b32_e64 v10, 1, -2, vcc
	v_lshl_add_u64 v[0:1], s[14:15], 0, v[144:145]
	v_lshl_add_u64 v[16:17], s[68:69], 0, v[144:145]
	v_mov_b32_e32 v5, v2
	v_cndmask_b32_e32 v3, v97, v155, vcc
	v_cndmask_b32_e32 v2, v96, v154, vcc
	v_add_u32_e32 v144, v10, v156
	v_cndmask_b32_e32 v115, v166, v167, vcc
	v_cndmask_b32_e32 v9, v1, v17, vcc
	v_cndmask_b32_e32 v8, v0, v16, vcc
	v_lshl_add_u64 v[104:105], v[2:3], 0, v[144:145]
	v_mul_lo_u32 v105, v105, v115
	v_mad_u64_u32 v[2:3], s[4:5], v104, v115, v[8:9]
	v_add_u32_e32 v3, v105, v3
	global_load_dwordx4 v[4:7], v[4:5], off
	v_cmp_gt_u32_sdwa s[4:5], v148, v168 src0_sel:BYTE_0 src1_sel:DWORD
	global_load_dwordx4 v[8:11], v[2:3], off
	v_add_u32_e32 v100, -1, v156
	s_and_saveexec_b64 s[6:7], s[4:5]
	s_xor_b64 s[6:7], exec, s[6:7]
	v_mov_b32_e32 v101, v145
	v_lshl_add_u64 v[0:1], v[154:155], 0, v[100:101]
	v_mad_u64_u32 v[2:3], s[8:9], v0, s34, v[16:17]
	v_mov_b32_e32 v0, v3
	v_mad_u64_u32 v[0:1], s[8:9], v1, s34, v[0:1]
	v_mov_b32_e32 v3, v0
	s_or_saveexec_b64 s[6:7], s[6:7]
	v_mad_i64_i32 v[102:103], s[8:9], v12, s33, 0
	s_xor_b64 exec, exec, s[6:7]
	v_lshl_add_u64 v[0:1], v[0:1], 0, v[102:103]
	v_lshl_add_u64 v[2:3], v[0:1], 0, s[20:21]
	s_or_b64 exec, exec, s[6:7]
	v_or_b32_sdwa v179, v148, s35 dst_sel:DWORD dst_unused:UNUSED_PAD src0_sel:BYTE_0 src1_sel:DWORD
	v_lshrrev_b32_e32 v22, 4, v179
	v_add_u32_e32 v18, -3, v22
	v_or_b32_e32 v189, v154, v156
	v_or_b32_e32 v18, v154, v18
	v_add_u32_e32 v20, -2, v22
	v_mul_lo_u32 v183, v155, s34
	v_mad_u64_u32 v[0:1], s[6:7], v189, s34, v[16:17]
	v_mad_u64_u32 v[18:19], s[6:7], v18, s34, v[16:17]
	v_or_b32_e32 v20, v154, v20
	v_add_u32_e32 v1, v183, v1
	v_add_u32_e32 v19, v183, v19
	v_mad_u64_u32 v[20:21], s[6:7], v20, s34, v[16:17]
	global_load_dwordx4 v[12:15], v[2:3], off
	v_add_u32_e32 v21, v183, v21
	global_load_dwordx4 v[0:3], v[0:1], off
	s_nop 0
	global_load_dwordx4 v[52:55], v[18:19], off
	global_load_dwordx4 v[48:51], v[20:21], off
	v_add_u32_e32 v18, -1, v22
	v_or_b32_e32 v18, v154, v18
	v_or_b32_e32 v184, v154, v22
	v_mad_u64_u32 v[18:19], s[6:7], v18, s34, v[16:17]
	v_or_b32_sdwa v178, v148, s23 dst_sel:DWORD dst_unused:UNUSED_PAD src0_sel:BYTE_0 src1_sel:DWORD
	v_add_u32_e32 v19, v183, v19
	v_mad_u64_u32 v[20:21], s[6:7], v184, s34, v[16:17]
	v_lshrrev_b32_e32 v22, 4, v178
	v_add_u32_e32 v21, v183, v21
	global_load_dwordx4 v[60:63], v[18:19], off
	global_load_dwordx4 v[56:59], v[20:21], off
	v_add_u32_e32 v18, -3, v22
	v_or_b32_e32 v18, v154, v18
	v_add_u32_e32 v20, -2, v22
	v_mad_u64_u32 v[18:19], s[6:7], v18, s34, v[16:17]
	v_or_b32_e32 v20, v154, v20
	v_add_u32_e32 v19, v183, v19
	v_mad_u64_u32 v[20:21], s[6:7], v20, s34, v[16:17]
	v_add_u32_e32 v21, v183, v21
	global_load_dwordx4 v[68:71], v[18:19], off
	global_load_dwordx4 v[64:67], v[20:21], off
	v_add_u32_e32 v18, -1, v22
	v_or_b32_e32 v18, v154, v18
	v_or_b32_e32 v185, v154, v22
	v_mad_u64_u32 v[18:19], s[6:7], v18, s34, v[16:17]
	v_or_b32_sdwa v153, v148, s36 dst_sel:DWORD dst_unused:UNUSED_PAD src0_sel:BYTE_0 src1_sel:DWORD
	v_add_u32_e32 v19, v183, v19
	v_mad_u64_u32 v[20:21], s[6:7], v185, s34, v[16:17]
	v_lshrrev_b32_e32 v22, 4, v153
	v_add_u32_e32 v21, v183, v21
	global_load_dwordx4 v[76:79], v[18:19], off
	global_load_dwordx4 v[72:75], v[20:21], off
	v_add_u32_e32 v18, -3, v22
	v_or_b32_e32 v18, v154, v18
	v_add_u32_e32 v20, -2, v22
	v_mad_u64_u32 v[18:19], s[6:7], v18, s34, v[16:17]
	v_or_b32_e32 v20, v154, v20
	v_add_u32_e32 v19, v183, v19
	v_mad_u64_u32 v[20:21], s[6:7], v20, s34, v[16:17]
	v_add_u32_e32 v21, v183, v21
	global_load_dwordx4 v[88:91], v[18:19], off
	global_load_dwordx4 v[80:83], v[20:21], off
	v_add_u32_e32 v18, -1, v22
	v_or_b32_e32 v18, v154, v18
	v_or_b32_e32 v186, v154, v22
	v_mad_u64_u32 v[18:19], s[6:7], v18, s34, v[16:17]
	v_add_u32_e32 v19, v183, v19
	v_mad_u64_u32 v[16:17], s[6:7], v186, s34, v[16:17]
	v_add_u32_e32 v17, v183, v17
	global_load_dwordx4 v[92:95], v[18:19], off
	global_load_dwordx4 v[84:87], v[16:17], off
	v_lshl_add_u32 v147, v180, 2, 0
	ds_read_b128 v[44:47], v147
	ds_read_b128 v[28:31], v147 offset:16
	ds_read_b128 v[24:27], v147 offset:1040
	ds_read_b128 v[40:43], v147 offset:1024
	ds_read_b128 v[20:23], v147 offset:2064
	ds_read_b128 v[36:39], v147 offset:2048
	ds_read_b128 v[16:19], v147 offset:3088
	ds_read_b128 v[32:35], v147 offset:3072
	v_mov_b32_e32 v157, v145
	v_mov_b64_e32 v[108:109], 0x20600000
	v_mov_b64_e32 v[106:107], 0x5000
	v_mov_b64_e32 v[110:111], v[156:157]
	s_and_saveexec_b64 s[6:7], s[0:1]
	v_mov_b32_e32 v99, v145
	v_mov_b64_e32 v[108:109], 0x8100000
	v_mov_b64_e32 v[106:107], 0x6000
	v_mov_b64_e32 v[110:111], v[98:99]
	v_mov_b64_e32 v[96:97], v[154:155]
	s_or_b64 exec, exec, s[6:7]
	v_mad_u64_u32 v[120:121], s[0:1], v104, v115, 0
	v_add_u32_e32 v121, v121, v105
	v_lshl_or_b32 v144, v114, 1, v169
	v_lshl_add_u64 v[104:105], s[82:83], 0, v[108:109]
	v_lshl_add_u64 v[104:105], v[104:105], 0, v[144:145]
	v_lshl_add_u64 v[96:97], v[96:97], 0, v[110:111]
	v_mad_u64_u32 v[104:105], s[0:1], v96, v106, v[104:105]
	v_mov_b32_e32 v96, v105
	v_lshl_add_u64 v[98:99], s[14:15], 0, v[144:145]
	v_lshl_add_u64 v[158:159], s[68:69], 0, v[144:145]
	v_mad_u64_u32 v[96:97], s[0:1], v97, v106, v[96:97]
	v_mov_b32_e32 v105, v96
	v_cndmask_b32_e32 v97, v99, v159, vcc
	v_cndmask_b32_e32 v96, v98, v158, vcc
	v_lshl_add_u64 v[96:97], v[96:97], 0, v[120:121]
	global_load_dwordx4 v[116:119], v[104:105], off
	global_load_dwordx4 v[120:123], v[96:97], off
	s_and_saveexec_b64 s[0:1], s[4:5]
	s_xor_b64 s[0:1], exec, s[0:1]
	v_mov_b32_e32 v101, v145
	v_lshl_add_u64 v[98:99], v[154:155], 0, v[100:101]
	v_mad_u64_u32 v[96:97], s[4:5], v98, s34, v[158:159]
	v_mov_b32_e32 v98, v97
	v_mad_u64_u32 v[98:99], s[4:5], v99, s34, v[98:99]
	v_mov_b32_e32 v97, v98
	s_andn2_saveexec_b64 s[0:1], s[0:1]
	v_lshl_add_u64 v[96:97], v[98:99], 0, v[102:103]
	v_lshl_add_u64 v[96:97], v[96:97], 0, s[20:21]
	s_or_b64 exec, exec, s[0:1]
	v_mad_u64_u32 v[150:151], s[0:1], v189, s34, 0
	global_load_dwordx4 v[124:127], v[96:97], off
	v_add_u32_e32 v151, v151, v183
	v_lshl_add_u64 v[96:97], v[158:159], 0, v[150:151]
	global_load_dwordx4 v[96:99], v[96:97], off
	v_cmp_eq_u32_e32 vcc, 0, v113
	v_cmp_lt_u32_sdwa s[4:5], v148, v170 src0_sel:BYTE_0 src1_sel:DWORD
	v_add_u32_e32 v188, 13, v156
	v_add_u32_e32 v191, 14, v156
	s_and_b64 s[26:27], s[4:5], vcc
	v_cmp_lt_u32_sdwa s[0:1], v148, v171 src0_sel:BYTE_0 src1_sel:DWORD
	v_or_b32_e32 v187, 16, v189
	v_add_u32_e32 v192, 15, v156
	v_or_b32_e32 v190, 48, v156
	s_waitcnt vmcnt(3)
	v_cndmask_b32_e64 v218, v119, 0, s[26:27]
	v_or_b32_e32 v119, v154, v188
	v_or_b32_e32 v191, v154, v191
	s_and_b64 s[24:25], s[0:1], vcc
	v_or_b32_e32 v194, v154, v192
	v_mad_u64_u32 v[192:193], s[0:1], v187, s34, v[158:159]
	v_or_b32_e32 v188, v154, v190
	v_cndmask_b32_e64 v220, v118, 0, s[26:27]
	v_cndmask_b32_e64 v195, v117, 0, s[26:27]
	v_cndmask_b32_e64 v196, v116, 0, s[26:27]
	v_mad_u64_u32 v[116:117], s[0:1], v119, s34, v[158:159]
	v_mad_u64_u32 v[118:119], s[0:1], v191, s34, v[158:159]
	s_waitcnt vmcnt(2)
	v_cndmask_b32_e64 v197, v121, 0, s[24:25]
	v_cndmask_b32_e64 v198, v120, 0, s[24:25]
	v_mad_u64_u32 v[120:121], s[0:1], v194, s34, v[158:159]
	v_add_u32_e32 v193, v183, v193
	v_mad_u64_u32 v[208:209], s[0:1], v188, s34, v[158:159]
	v_add_u32_e32 v117, v183, v117
	v_add_u32_e32 v119, v183, v119
	v_mul_i32_i24_e32 v157, 0x4400, v112
	ds_read_b128 v[136:139], v147 offset:512
	ds_read_b128 v[104:107], v147 offset:528
	v_or_b32_e32 v144, v113, v156
	ds_read_b128 v[112:115], v147 offset:1552
	ds_read_b128 v[140:143], v147 offset:1536
	ds_read_b128 v[108:111], v147 offset:2576
	ds_read_b128 v[132:135], v147 offset:2560
	ds_read_b128 v[100:103], v147 offset:3600
	ds_read_b128 v[128:131], v147 offset:3584
	v_lshlrev_b32_e32 v210, 16, v196
	v_and_b32_e32 v211, 0xffff0000, v196
	v_lshlrev_b32_e32 v212, 16, v198
	v_and_b32_e32 v213, 0xffff0000, v198
	v_lshlrev_b32_e32 v214, 16, v195
	v_and_b32_e32 v215, 0xffff0000, v195
	v_lshlrev_b32_e32 v216, 16, v197
	v_and_b32_e32 v217, 0xffff0000, v197
	v_add_u32_e32 v121, v183, v121
	global_load_dwordx4 v[192:195], v[192:193], off
	v_add_u32_e32 v209, v183, v209
	global_load_dwordx4 v[196:199], v[116:117], off
	global_load_dwordx4 v[200:203], v[118:119], off
	global_load_dwordx4 v[204:207], v[120:121], off
	s_nop 0
	global_load_dwordx4 v[116:119], v[208:209], off
	v_cmp_eq_u32_e64 s[4:5], 0, v144
	s_waitcnt lgkmcnt(7)
	v_pk_fma_f32 v[120:121], v[136:137], v[210:211], 0 op_sel_hi:[1,1,0]
	v_pk_fma_f32 v[136:137], v[138:139], v[214:215], 0 op_sel_hi:[1,1,0]
	s_waitcnt lgkmcnt(4)
	v_pk_fma_f32 v[120:121], v[140:141], v[212:213], v[120:121]
	v_pk_fma_f32 v[136:137], v[142:143], v[216:217], v[136:137]
	v_cndmask_b32_e64 v122, v122, 0, s[24:25]
	v_cndmask_b32_e64 v219, v123, 0, s[24:25]
	v_add_u32_e32 v157, 0, v157
	v_lshl_add_u32 v123, v180, 1, v157
	s_waitcnt vmcnt(6)
	v_cndmask_b32_e64 v124, v124, 0, s[4:5]
	v_cndmask_b32_e64 v138, v127, 0, s[4:5]
	v_cndmask_b32_e64 v139, v126, 0, s[4:5]
	v_lshlrev_b32_e32 v126, 16, v124
	v_and_b32_e32 v127, 0xffff0000, v124
	s_waitcnt lgkmcnt(2)
	v_pk_fma_f32 v[120:121], v[132:133], v[126:127], v[120:121]
	s_waitcnt vmcnt(5)
	v_lshlrev_b32_e32 v126, 16, v96
	v_and_b32_e32 v127, 0xffff0000, v96
	s_waitcnt lgkmcnt(0)
	v_pk_fma_f32 v[120:121], v[128:129], v[126:127], v[120:121]
	v_cndmask_b32_e64 v125, v125, 0, s[4:5]
	v_mul_f32_e32 v96, 0xbfb8aa3b, v121
	v_mul_f32_e32 v124, 0xbfb8aa3b, v120
	v_exp_f32_e32 v96, v96
	v_exp_f32_e32 v126, v124
	v_lshlrev_b32_e32 v124, 16, v125
	v_and_b32_e32 v125, 0xffff0000, v125
	v_add_f32_e32 v96, 1.0, v96
	v_add_f32_e32 v126, 1.0, v126
	v_rcp_f32_e32 v127, v96
	v_rcp_f32_e32 v126, v126
	v_pk_fma_f32 v[124:125], v[134:135], v[124:125], v[136:137]
	v_lshlrev_b32_e32 v96, 16, v97
	v_and_b32_e32 v97, 0xffff0000, v97
	v_pk_fma_f32 v[124:125], v[130:131], v[96:97], v[124:125]
	v_pk_mul_f32 v[120:121], v[120:121], v[126:127]
	v_mul_f32_e32 v96, 0xbfb8aa3b, v125
	v_exp_f32_e32 v97, v96
	v_mul_f32_e32 v96, 0xbfb8aa3b, v124
	v_exp_f32_e32 v126, v96
	v_cvt_pk_bf16_f32 v96, v120, v121
	v_add_f32_e32 v97, 1.0, v97
	v_rcp_f32_e32 v121, v97
	v_add_f32_e32 v97, 1.0, v126
	v_lshlrev_b32_e32 v126, 16, v220
	v_and_b32_e32 v127, 0xffff0000, v220
	v_pk_fma_f32 v[104:105], v[104:105], v[126:127], 0 op_sel_hi:[1,1,0]
	v_lshlrev_b32_e32 v126, 16, v122
	v_and_b32_e32 v127, 0xffff0000, v122
	v_pk_fma_f32 v[104:105], v[112:113], v[126:127], v[104:105]
	v_lshlrev_b32_e32 v112, 16, v139
	v_and_b32_e32 v113, 0xffff0000, v139
	v_pk_fma_f32 v[104:105], v[108:109], v[112:113], v[104:105]
	v_lshlrev_b32_e32 v108, 16, v98
	v_and_b32_e32 v109, 0xffff0000, v98
	v_pk_fma_f32 v[100:101], v[100:101], v[108:109], v[104:105]
	v_rcp_f32_e32 v120, v97
	v_mul_f32_e32 v97, 0xbfb8aa3b, v101
	v_exp_f32_e32 v97, v97
	v_mul_f32_e32 v98, 0xbfb8aa3b, v100
	v_exp_f32_e32 v98, v98
	v_lshlrev_b32_e32 v112, 16, v218
	v_and_b32_e32 v113, 0xffff0000, v218
	v_pk_fma_f32 v[106:107], v[106:107], v[112:113], 0 op_sel_hi:[1,1,0]
	v_lshlrev_b32_e32 v112, 16, v219
	v_and_b32_e32 v113, 0xffff0000, v219
	v_add_f32_e32 v97, 1.0, v97
	v_pk_fma_f32 v[106:107], v[114:115], v[112:113], v[106:107]
	v_lshlrev_b32_e32 v112, 16, v138
	v_and_b32_e32 v113, 0xffff0000, v138
	v_rcp_f32_e32 v109, v97
	v_add_f32_e32 v97, 1.0, v98
	v_pk_fma_f32 v[106:107], v[110:111], v[112:113], v[106:107]
	v_lshlrev_b32_e32 v98, 16, v99
	v_and_b32_e32 v99, 0xffff0000, v99
	v_pk_fma_f32 v[102:103], v[102:103], v[98:99], v[106:107]
	v_rcp_f32_e32 v108, v97
	v_mul_f32_e32 v98, 0xbfb8aa3b, v103
	v_exp_f32_e32 v98, v98
	v_mul_f32_e32 v99, 0xbfb8aa3b, v102
	v_exp_f32_e32 v99, v99
	v_pk_mul_f32 v[104:105], v[124:125], v[120:121]
	v_add_f32_e32 v97, 1.0, v98
	v_rcp_f32_e32 v107, v97
	v_add_f32_e32 v97, 1.0, v99
	v_rcp_f32_e32 v106, v97
	v_pk_mul_f32 v[98:99], v[100:101], v[108:109]
	v_cvt_pk_bf16_f32 v97, v104, v105
	v_cvt_pk_bf16_f32 v98, v98, v99
	v_pk_mul_f32 v[100:101], v[102:103], v[106:107]
	v_mad_u32_u24 v122, v156, s38, v123
	v_cvt_pk_bf16_f32 v99, v100, v101
	ds_write_b128 v122, v[96:99] offset:4096
	ds_read_b128 v[100:103], v147 offset:512
	ds_read_b128 v[104:107], v147 offset:528
	ds_read_b128 v[108:111], v147 offset:1536
	ds_read_b128 v[112:115], v147 offset:2560
	ds_read_b128 v[124:127], v147 offset:3584
	s_waitcnt vmcnt(3)
	v_lshlrev_b32_e32 v120, 16, v196
	v_and_b32_e32 v121, 0xffff0000, v196
	s_waitcnt lgkmcnt(4)
	v_pk_fma_f32 v[100:101], v[100:101], v[120:121], 0 op_sel_hi:[1,1,0]
	s_waitcnt vmcnt(2)
	v_lshlrev_b32_e32 v120, 16, v200
	v_and_b32_e32 v121, 0xffff0000, v200
	s_waitcnt lgkmcnt(2)
	v_pk_fma_f32 v[100:101], v[108:109], v[120:121], v[100:101]
	s_waitcnt vmcnt(1)
	v_lshlrev_b32_e32 v108, 16, v204
	v_and_b32_e32 v109, 0xffff0000, v204
	s_waitcnt lgkmcnt(1)
	v_pk_fma_f32 v[100:101], v[112:113], v[108:109], v[100:101]
	v_add_u32_e32 v108, 29, v156
	v_or_b32_e32 v108, v154, v108
	v_mad_u64_u32 v[108:109], s[0:1], v108, s34, v[158:159]
	v_add_u32_e32 v109, v183, v109
	global_load_dwordx4 v[128:131], v[108:109], off
	v_lshlrev_b32_e32 v108, 16, v192
	v_and_b32_e32 v109, 0xffff0000, v192
	s_waitcnt lgkmcnt(0)
	v_pk_fma_f32 v[100:101], v[124:125], v[108:109], v[100:101]
	ds_read_b128 v[132:135], v147 offset:1552
	ds_read_b128 v[136:139], v147 offset:2576
	ds_read_b128 v[140:143], v147 offset:3600
	v_mul_f32_e32 v108, 0xbfb8aa3b, v101
	v_exp_f32_e32 v108, v108
	v_mul_f32_e32 v109, 0xbfb8aa3b, v100
	v_exp_f32_e32 v112, v109
	v_lshlrev_b32_e32 v120, 16, v198
	v_add_f32_e32 v108, 1.0, v108
	v_rcp_f32_e32 v109, v108
	v_add_f32_e32 v108, 1.0, v112
	v_add_u32_e32 v112, 30, v156
	v_or_b32_e32 v112, v154, v112
	v_rcp_f32_e32 v108, v108
	v_mad_u64_u32 v[112:113], s[0:1], v112, s34, v[158:159]
	v_add_u32_e32 v113, v183, v113
	global_load_dwordx4 v[208:211], v[112:113], off
	v_add_u32_e32 v112, 31, v156
	v_or_b32_e32 v112, v154, v112
	v_pk_mul_f32 v[100:101], v[100:101], v[108:109]
	v_lshlrev_b32_e32 v108, 16, v197
	v_and_b32_e32 v109, 0xffff0000, v197
	v_mad_u64_u32 v[112:113], s[0:1], v112, s34, v[158:159]
	v_pk_fma_f32 v[102:103], v[102:103], v[108:109], 0 op_sel_hi:[1,1,0]
	v_lshlrev_b32_e32 v108, 16, v201
	v_and_b32_e32 v109, 0xffff0000, v201
	v_add_u32_e32 v113, v183, v113
	global_load_dwordx4 v[212:215], v[112:113], off
	v_pk_fma_f32 v[102:103], v[110:111], v[108:109], v[102:103]
	v_lshlrev_b32_e32 v108, 16, v205
	v_and_b32_e32 v109, 0xffff0000, v205
	v_or_b32_e32 v112, 32, v189
	v_pk_fma_f32 v[102:103], v[114:115], v[108:109], v[102:103]
	v_mad_u64_u32 v[108:109], s[0:1], v112, s34, v[158:159]
	v_add_u32_e32 v109, v183, v109
	global_load_dwordx4 v[108:111], v[108:109], off
	v_lshlrev_b32_e32 v114, 16, v193
	v_and_b32_e32 v115, 0xffff0000, v193
	v_pk_fma_f32 v[102:103], v[126:127], v[114:115], v[102:103]
	v_and_b32_e32 v121, 0xffff0000, v198
	v_mul_f32_e32 v113, 0xbfb8aa3b, v103
	v_exp_f32_e32 v113, v113
	v_mul_f32_e32 v114, 0xbfb8aa3b, v102
	v_exp_f32_e32 v114, v114
	v_pk_fma_f32 v[104:105], v[104:105], v[120:121], 0 op_sel_hi:[1,1,0]
	v_lshlrev_b32_e32 v120, 16, v202
	v_and_b32_e32 v121, 0xffff0000, v202
	s_waitcnt lgkmcnt(2)
	v_pk_fma_f32 v[104:105], v[132:133], v[120:121], v[104:105]
	v_lshlrev_b32_e32 v120, 16, v206
	v_and_b32_e32 v121, 0xffff0000, v206
	v_cvt_pk_bf16_f32 v100, v100, v101
	v_add_f32_e32 v101, 1.0, v113
	s_waitcnt lgkmcnt(1)
	v_pk_fma_f32 v[104:105], v[136:137], v[120:121], v[104:105]
	v_lshlrev_b32_e32 v120, 16, v194
	v_and_b32_e32 v121, 0xffff0000, v194
	v_rcp_f32_e32 v115, v101
	v_add_f32_e32 v101, 1.0, v114
	s_waitcnt lgkmcnt(0)
	v_pk_fma_f32 v[104:105], v[140:141], v[120:121], v[104:105]
	v_rcp_f32_e32 v114, v101
	v_mul_f32_e32 v101, 0xbfb8aa3b, v105
	v_exp_f32_e32 v101, v101
	v_mul_f32_e32 v113, 0xbfb8aa3b, v104
	v_lshlrev_b32_e32 v120, 16, v199
	v_and_b32_e32 v121, 0xffff0000, v199
	v_exp_f32_e32 v113, v113
	v_pk_fma_f32 v[106:107], v[106:107], v[120:121], 0 op_sel_hi:[1,1,0]
	v_lshlrev_b32_e32 v120, 16, v203
	v_and_b32_e32 v121, 0xffff0000, v203
	v_pk_fma_f32 v[106:107], v[134:135], v[120:121], v[106:107]
	v_lshlrev_b32_e32 v120, 16, v207
	v_and_b32_e32 v121, 0xffff0000, v207
	v_pk_fma_f32 v[106:107], v[138:139], v[120:121], v[106:107]
	v_lshlrev_b32_e32 v120, 16, v195
	v_and_b32_e32 v121, 0xffff0000, v195
	v_add_f32_e32 v101, 1.0, v101
	v_pk_fma_f32 v[106:107], v[142:143], v[120:121], v[106:107]
	v_pk_mul_f32 v[102:103], v[102:103], v[114:115]
	v_rcp_f32_e32 v115, v101
	v_add_f32_e32 v101, 1.0, v113
	v_mul_f32_e32 v113, 0xbfb8aa3b, v107
	v_exp_f32_e32 v113, v113
	v_mul_f32_e32 v114, 0xbfb8aa3b, v106
	v_exp_f32_e32 v120, v114
	v_rcp_f32_e32 v114, v101
	v_add_f32_e32 v101, 1.0, v113
	v_rcp_f32_e32 v121, v101
	v_add_f32_e32 v101, 1.0, v120
	v_rcp_f32_e32 v120, v101
	v_cvt_pk_bf16_f32 v101, v102, v103
	v_pk_mul_f32 v[102:103], v[104:105], v[114:115]
	s_waitcnt vmcnt(3)
	v_lshlrev_b32_e32 v114, 16, v128
	v_pk_mul_f32 v[104:105], v[106:107], v[120:121]
	v_cvt_pk_bf16_f32 v102, v102, v103
	v_cvt_pk_bf16_f32 v103, v104, v105
	ds_write_b128 v122, v[100:103] offset:8448
	ds_read_b128 v[104:107], v147 offset:512
	ds_read_b128 v[124:127], v147 offset:528
	ds_read_b128 v[132:135], v147 offset:1536
	ds_read_b128 v[136:139], v147 offset:2560
	ds_read_b128 v[140:143], v147 offset:3584
	v_and_b32_e32 v115, 0xffff0000, v128
	s_waitcnt lgkmcnt(4)
	v_pk_fma_f32 v[104:105], v[104:105], v[114:115], 0 op_sel_hi:[1,1,0]
	s_waitcnt vmcnt(2)
	v_lshlrev_b32_e32 v114, 16, v208
	v_and_b32_e32 v115, 0xffff0000, v208
	v_add_u32_e32 v113, 45, v156
	s_waitcnt lgkmcnt(2)
	v_pk_fma_f32 v[104:105], v[132:133], v[114:115], v[104:105]
	v_or_b32_e32 v113, v154, v113
	v_lshlrev_b32_e32 v120, 16, v210
	v_and_b32_e32 v121, 0xffff0000, v210
	s_waitcnt vmcnt(1)
	v_lshlrev_b32_e32 v114, 16, v212
	v_and_b32_e32 v115, 0xffff0000, v212
	s_waitcnt lgkmcnt(1)
	v_pk_fma_f32 v[104:105], v[136:137], v[114:115], v[104:105]
	v_mad_u64_u32 v[114:115], s[0:1], v113, s34, v[158:159]
	v_add_u32_e32 v115, v183, v115
	global_load_dwordx4 v[192:195], v[114:115], off
	ds_read_b128 v[196:199], v147 offset:1552
	ds_read_b128 v[200:203], v147 offset:2576
	ds_read_b128 v[204:207], v147 offset:3600
	s_waitcnt vmcnt(1)
	v_lshlrev_b32_e32 v114, 16, v108
	v_and_b32_e32 v115, 0xffff0000, v108
	s_waitcnt lgkmcnt(3)
	v_pk_fma_f32 v[104:105], v[140:141], v[114:115], v[104:105]
	s_nop 0
	v_mul_f32_e32 v108, 0xbfb8aa3b, v105
	v_exp_f32_e32 v108, v108
	v_mul_f32_e32 v113, 0xbfb8aa3b, v104
	v_exp_f32_e32 v113, v113
	v_add_f32_e32 v108, 1.0, v108
	v_rcp_f32_e32 v115, v108
	v_add_f32_e32 v108, 1.0, v113
	v_rcp_f32_e32 v114, v108
	v_add_u32_e32 v108, 46, v156
	v_or_b32_e32 v108, v154, v108
	v_pk_mul_f32 v[104:105], v[104:105], v[114:115]
	v_mad_u64_u32 v[114:115], s[0:1], v108, s34, v[158:159]
	v_add_u32_e32 v108, 47, v156
	v_add_u32_e32 v115, v183, v115
	v_or_b32_e32 v108, v154, v108
	global_load_dwordx4 v[216:219], v[114:115], off
	v_mad_u64_u32 v[114:115], s[0:1], v108, s34, v[158:159]
	v_add_u32_e32 v115, v183, v115
	global_load_dwordx4 v[220:223], v[114:115], off
	v_lshlrev_b32_e32 v114, 16, v129
	v_and_b32_e32 v115, 0xffff0000, v129
	v_pk_fma_f32 v[106:107], v[106:107], v[114:115], 0 op_sel_hi:[1,1,0]
	v_lshlrev_b32_e32 v114, 16, v209
	v_and_b32_e32 v115, 0xffff0000, v209
	v_pk_fma_f32 v[106:107], v[134:135], v[114:115], v[106:107]
	v_lshlrev_b32_e32 v114, 16, v213
	v_and_b32_e32 v115, 0xffff0000, v213
	v_pk_fma_f32 v[106:107], v[138:139], v[114:115], v[106:107]
	v_lshlrev_b32_e32 v108, 16, v109
	v_and_b32_e32 v109, 0xffff0000, v109
	v_pk_fma_f32 v[106:107], v[142:143], v[108:109], v[106:107]
	v_lshlrev_b32_e32 v114, 16, v130
	v_mul_f32_e32 v108, 0xbfb8aa3b, v107
	v_exp_f32_e32 v108, v108
	v_mul_f32_e32 v109, 0xbfb8aa3b, v106
	v_exp_f32_e32 v113, v109
	v_and_b32_e32 v115, 0xffff0000, v130
	v_pk_fma_f32 v[114:115], v[124:125], v[114:115], 0 op_sel_hi:[1,1,0]
	v_cvt_pk_bf16_f32 v104, v104, v105
	s_waitcnt lgkmcnt(2)
	v_pk_fma_f32 v[114:115], v[196:197], v[120:121], v[114:115]
	v_lshlrev_b32_e32 v120, 16, v214
	v_and_b32_e32 v121, 0xffff0000, v214
	v_add_f32_e32 v105, 1.0, v108
	s_waitcnt lgkmcnt(1)
	v_pk_fma_f32 v[114:115], v[200:201], v[120:121], v[114:115]
	v_lshlrev_b32_e32 v120, 16, v110
	v_and_b32_e32 v121, 0xffff0000, v110
	v_rcp_f32_e32 v109, v105
	v_add_f32_e32 v105, 1.0, v113
	s_waitcnt lgkmcnt(0)
	v_pk_fma_f32 v[114:115], v[204:205], v[120:121], v[114:115]
	v_rcp_f32_e32 v108, v105
	v_mul_f32_e32 v105, 0xbfb8aa3b, v115
	v_exp_f32_e32 v105, v105
	v_mul_f32_e32 v110, 0xbfb8aa3b, v114
	v_exp_f32_e32 v110, v110
	v_lshlrev_b32_e32 v120, 16, v131
	v_and_b32_e32 v121, 0xffff0000, v131
	v_pk_fma_f32 v[120:121], v[126:127], v[120:121], 0 op_sel_hi:[1,1,0]
	v_lshlrev_b32_e32 v124, 16, v211
	v_and_b32_e32 v125, 0xffff0000, v211
	v_add_f32_e32 v105, 1.0, v105
	v_pk_fma_f32 v[120:121], v[198:199], v[124:125], v[120:121]
	v_lshlrev_b32_e32 v124, 16, v215
	v_and_b32_e32 v125, 0xffff0000, v215
	v_pk_mul_f32 v[106:107], v[106:107], v[108:109]
	v_rcp_f32_e32 v109, v105
	v_add_f32_e32 v105, 1.0, v110
	v_pk_fma_f32 v[120:121], v[202:203], v[124:125], v[120:121]
	v_lshlrev_b32_e32 v110, 16, v111
	v_and_b32_e32 v111, 0xffff0000, v111
	v_pk_fma_f32 v[110:111], v[206:207], v[110:111], v[120:121]
	s_nop 0
	v_mul_f32_e32 v108, 0xbfb8aa3b, v111
	v_exp_f32_e32 v113, v108
	v_mul_f32_e32 v108, 0xbfb8aa3b, v110
	v_exp_f32_e32 v120, v108
	v_rcp_f32_e32 v108, v105
	v_add_f32_e32 v105, 1.0, v113
	v_rcp_f32_e32 v121, v105
	v_add_f32_e32 v105, 1.0, v120
	v_rcp_f32_e32 v120, v105
	v_cvt_pk_bf16_f32 v105, v106, v107
	v_pk_mul_f32 v[106:107], v[114:115], v[108:109]
	s_waitcnt vmcnt(2)
	v_lshlrev_b32_e32 v114, 16, v192
	v_pk_mul_f32 v[108:109], v[110:111], v[120:121]
	v_cvt_pk_bf16_f32 v106, v106, v107
	v_cvt_pk_bf16_f32 v107, v108, v109
	ds_write_b128 v122, v[104:107] offset:12800
	ds_read_b128 v[108:111], v147 offset:512
	ds_read_b128 v[124:127], v147 offset:528
	ds_read_b128 v[128:131], v147 offset:1536
	ds_read_b128 v[132:135], v147 offset:2560
	ds_read_b128 v[136:139], v147 offset:3584
	v_and_b32_e32 v115, 0xffff0000, v192
	s_waitcnt lgkmcnt(4)
	v_pk_fma_f32 v[108:109], v[108:109], v[114:115], 0 op_sel_hi:[1,1,0]
	ds_read_b128 v[140:143], v147 offset:1552
	ds_read_b128 v[196:199], v147 offset:2576
	ds_read_b128 v[200:203], v147 offset:3600
	s_waitcnt vmcnt(1)
	v_lshlrev_b32_e32 v114, 16, v216
	v_and_b32_e32 v115, 0xffff0000, v216
	s_waitcnt lgkmcnt(5)
	v_pk_fma_f32 v[108:109], v[128:129], v[114:115], v[108:109]
	v_lshlrev_b32_e32 v120, 16, v218
	s_waitcnt vmcnt(0)
	v_lshlrev_b32_e32 v114, 16, v220
	v_and_b32_e32 v115, 0xffff0000, v220
	s_waitcnt lgkmcnt(4)
	v_pk_fma_f32 v[108:109], v[132:133], v[114:115], v[108:109]
	v_lshlrev_b32_e32 v114, 16, v116
	v_and_b32_e32 v115, 0xffff0000, v116
	s_waitcnt lgkmcnt(3)
	v_pk_fma_f32 v[108:109], v[136:137], v[114:115], v[108:109]
	v_lshlrev_b32_e32 v116, 16, v194
	v_mul_f32_e32 v113, 0xbfb8aa3b, v109
	v_exp_f32_e32 v113, v113
	v_mul_f32_e32 v114, 0xbfb8aa3b, v108
	v_exp_f32_e32 v114, v114
	v_and_b32_e32 v121, 0xffff0000, v218
	v_add_f32_e32 v113, 1.0, v113
	v_rcp_f32_e32 v115, v113
	v_add_f32_e32 v113, 1.0, v114
	v_rcp_f32_e32 v114, v113
	s_nop 0
	v_pk_mul_f32 v[108:109], v[108:109], v[114:115]
	v_lshlrev_b32_e32 v114, 16, v193
	v_and_b32_e32 v115, 0xffff0000, v193
	v_pk_fma_f32 v[110:111], v[110:111], v[114:115], 0 op_sel_hi:[1,1,0]
	v_lshlrev_b32_e32 v114, 16, v217
	v_and_b32_e32 v115, 0xffff0000, v217
	v_pk_fma_f32 v[110:111], v[130:131], v[114:115], v[110:111]
	v_lshlrev_b32_e32 v114, 16, v221
	v_and_b32_e32 v115, 0xffff0000, v221
	v_pk_fma_f32 v[110:111], v[134:135], v[114:115], v[110:111]
	v_lshlrev_b32_e32 v114, 16, v117
	v_and_b32_e32 v115, 0xffff0000, v117
	v_pk_fma_f32 v[110:111], v[138:139], v[114:115], v[110:111]
	v_and_b32_e32 v117, 0xffff0000, v194
	v_mul_f32_e32 v113, 0xbfb8aa3b, v111
	v_exp_f32_e32 v113, v113
	v_mul_f32_e32 v114, 0xbfb8aa3b, v110
	v_exp_f32_e32 v114, v114
	v_pk_fma_f32 v[116:117], v[124:125], v[116:117], 0 op_sel_hi:[1,1,0]
	v_cvt_pk_bf16_f32 v108, v108, v109
	s_waitcnt lgkmcnt(2)
	v_pk_fma_f32 v[116:117], v[140:141], v[120:121], v[116:117]
	v_lshlrev_b32_e32 v120, 16, v222
	v_and_b32_e32 v121, 0xffff0000, v222
	v_add_f32_e32 v109, 1.0, v113
	s_waitcnt lgkmcnt(1)
	v_pk_fma_f32 v[116:117], v[196:197], v[120:121], v[116:117]
	v_lshlrev_b32_e32 v120, 16, v118
	v_and_b32_e32 v121, 0xffff0000, v118
	v_rcp_f32_e32 v115, v109
	v_add_f32_e32 v109, 1.0, v114
	s_waitcnt lgkmcnt(0)
	v_pk_fma_f32 v[116:117], v[200:201], v[120:121], v[116:117]
	v_rcp_f32_e32 v114, v109
	v_mul_f32_e32 v109, 0xbfb8aa3b, v117
	v_exp_f32_e32 v109, v109
	v_mul_f32_e32 v113, 0xbfb8aa3b, v116
	v_lshlrev_b32_e32 v120, 16, v195
	v_and_b32_e32 v121, 0xffff0000, v195
	v_exp_f32_e32 v113, v113
	v_pk_fma_f32 v[120:121], v[126:127], v[120:121], 0 op_sel_hi:[1,1,0]
	v_lshlrev_b32_e32 v124, 16, v219
	v_and_b32_e32 v125, 0xffff0000, v219
	v_pk_fma_f32 v[120:121], v[142:143], v[124:125], v[120:121]
	v_lshlrev_b32_e32 v124, 16, v223
	v_and_b32_e32 v125, 0xffff0000, v223
	v_pk_fma_f32 v[120:121], v[198:199], v[124:125], v[120:121]
	v_lshlrev_b32_e32 v118, 16, v119
	v_and_b32_e32 v119, 0xffff0000, v119
	v_add_f32_e32 v109, 1.0, v109
	v_pk_fma_f32 v[118:119], v[202:203], v[118:119], v[120:121]
	v_pk_mul_f32 v[110:111], v[110:111], v[114:115]
	v_rcp_f32_e32 v115, v109
	v_add_f32_e32 v109, 1.0, v113
	v_mul_f32_e32 v113, 0xbfb8aa3b, v119
	v_exp_f32_e32 v113, v113
	v_mul_f32_e32 v114, 0xbfb8aa3b, v118
	v_exp_f32_e32 v120, v114
	v_rcp_f32_e32 v114, v109
	v_add_f32_e32 v109, 1.0, v113
	v_rcp_f32_e32 v121, v109
	v_add_f32_e32 v109, 1.0, v120
	v_rcp_f32_e32 v120, v109
	v_cvt_pk_bf16_f32 v109, v110, v111
	v_pk_mul_f32 v[110:111], v[116:117], v[114:115]
	v_mad_u32_u24 v113, v190, s38, v123
	v_pk_mul_f32 v[114:115], v[118:119], v[120:121]
	v_cvt_pk_bf16_f32 v110, v110, v111
	v_cvt_pk_bf16_f32 v111, v114, v115
	ds_write_b128 v113, v[108:111] offset:4096
	v_and_b32_e32 v113, 0xc0, v148
	v_cmp_eq_u32_e32 vcc, 0, v113
	s_and_saveexec_b64 s[28:29], vcc
	s_cbranch_execz .LBB0_327
	v_and_b32_e32 v113, 63, v148
	v_lshl_add_u64 v[114:115], v[154:155], 2, s[16:17]
	v_lshlrev_b32_e32 v144, 16, v181
	v_lshl_add_u64 v[114:115], v[114:115], 0, v[144:145]
	v_lshlrev_b32_e32 v144, 2, v113
	v_lshl_add_u64 v[114:115], v[114:115], 0, v[144:145]
	v_add_co_u32_e32 v116, vcc, 0x400000, v114
	s_mov_b64 s[0:1], vcc
	v_add_co_u32_e32 v118, vcc, 0x480000, v114
	v_readlane_b32 s48, v250, 19
	s_nop 0
	v_addc_co_u32_e32 v119, vcc, 0, v115, vcc
	v_lshlrev_b32_e32 v117, 2, v181
	s_waitcnt vmcnt(0)
	v_mov_b32_e32 v114, v226
	v_readlane_b32 s56, v250, 27
	v_readlane_b32 s57, v250, 28
	v_readlane_b32 s54, v250, 25
	v_readlane_b32 s55, v250, 26
	s_nop 2
	v_mov_b32_e32 v118, v228
	s_nop 0
	v_mov_b32_e32 v128, v229
	v_and_b32_e32 v129, 64, v173
	v_add_u32_e32 v117, -1, v173
	v_cmp_lt_i32_e32 vcc, v117, v129
	v_cmp_gt_u32_e64 s[12:13], 32, v113
	v_lshlrev_b32_e32 v144, 4, v182
	v_cndmask_b32_e32 v117, v117, v173, vcc
	v_lshlrev_b32_e32 v130, 2, v117
	v_readlane_b32 s49, v250, 20
	v_readlane_b32 s50, v250, 21
	v_readlane_b32 s51, v250, 22
	v_readlane_b32 s52, v250, 23
	v_readlane_b32 s53, v250, 24
	v_readlane_b32 s58, v250, 29
	v_readlane_b32 s59, v250, 30
	v_readlane_b32 s60, v250, 31
	v_readlane_b32 s61, v250, 32
	v_readlane_b32 s62, v250, 33
	v_readlane_b32 s63, v250, 34
	s_waitcnt vmcnt(1)
	v_add_f32_e32 v114, v114, v118
	v_mul_f32_e64 v117, |v114|, s37
	v_fma_f32 v118, |v114|, s37, -v117
	v_rndne_f32_e32 v119, v117
	v_fma_f32 v118, |v114|, s39, v118
	v_sub_f32_e32 v117, v117, v119
	v_add_f32_e32 v117, v117, v118
	v_cvt_i32_f32_e32 v119, v119
	v_exp_f32_e32 v118, v117
	v_addc_co_u32_e64 v117, vcc, 0, v115, s[0:1]
	v_cmp_ngt_f32_e64 vcc, |v114|, s40
	v_ldexp_f32 v115, v118, v119
	v_mov_b32_e32 v131, v227
	v_cndmask_b32_e32 v115, 0, v115, vcc
	v_cmp_nlt_f32_e64 vcc, |v114|, s41
	v_min_f32_e32 v132, 0, v114
	s_nop 0
	v_cndmask_b32_e32 v133, v172, v115, vcc
	v_add_f32_e32 v116, 1.0, v133
	v_add_f32_e32 v117, -1.0, v116
	v_frexp_mant_f32_e32 v118, v116
	v_cvt_f64_f32_e32 v[114:115], v116
	v_sub_f32_e32 v119, v117, v116
	v_frexp_exp_i32_f64_e32 v114, v[114:115]
	v_cmp_gt_f32_e32 vcc, s43, v118
	v_sub_f32_e32 v117, v133, v117
	v_add_f32_e32 v115, 1.0, v119
	v_subbrev_co_u32_e32 v114, vcc, 0, v114, vcc
	v_add_f32_e32 v115, v117, v115
	v_sub_u32_e32 v117, 0, v114
	v_ldexp_f32 v116, v116, v117
	v_add_f32_e32 v118, -1.0, v116
	v_add_f32_e32 v119, 1.0, v116
	v_ldexp_f32 v115, v115, v117
	v_add_f32_e32 v117, 1.0, v118
	v_add_f32_e32 v120, -1.0, v119
	v_sub_f32_e32 v117, v116, v117
	v_sub_f32_e32 v116, v116, v120
	v_add_f32_e32 v120, v115, v117
	v_add_f32_e32 v115, v115, v116
	v_add_f32_e32 v122, v119, v115
	v_rcp_f32_e32 v123, v122
	v_add_f32_e32 v117, v118, v120
	v_sub_f32_e32 v118, v118, v117
	v_sub_f32_e32 v116, v119, v122
	v_mul_f32_e32 v125, v117, v123
	v_add_f32_e32 v124, v120, v118
	v_mul_f32_e32 v118, v122, v125
	v_add_f32_e32 v115, v115, v116
	v_fma_f32 v120, v125, v122, -v118
	v_fmac_f32_e32 v120, v125, v115
	v_add_f32_e32 v116, v118, v120
	v_sub_f32_e32 v119, v117, v116
	v_mov_b32_e32 v121, v116
	v_pk_add_f32 v[116:117], v[116:117], v[118:119] neg_lo:[0,1] neg_hi:[0,1]
	v_cvt_f32_i32_e32 v114, v114
	v_pk_add_f32 v[116:117], v[116:117], v[120:121] neg_lo:[0,1] neg_hi:[0,1]
	v_cmp_neq_f32_e32 vcc, s42, v133
	v_add_f32_e32 v117, v124, v117
	v_add_f32_e32 v116, v116, v117
	v_add_f32_e32 v117, v119, v116
	v_mul_f32_e32 v121, v123, v117
	v_mul_f32_e32 v118, v122, v121
	v_sub_f32_e32 v119, v119, v117
	v_add_f32_e32 v126, v125, v121
	v_fma_f32 v120, v121, v122, -v118
	v_add_f32_e32 v124, v116, v119
	v_sub_f32_e32 v116, v126, v125
	v_fmac_f32_e32 v120, v121, v115
	v_sub_f32_e32 v115, v121, v116
	v_add_f32_e32 v116, v118, v120
	v_sub_f32_e32 v119, v117, v116
	v_mov_b32_e32 v121, v116
	v_pk_add_f32 v[116:117], v[116:117], v[118:119] neg_lo:[0,1] neg_hi:[0,1]
	s_nop 0
	v_pk_add_f32 v[116:117], v[116:117], v[120:121] neg_lo:[0,1] neg_hi:[0,1]
	s_nop 0
	v_add_f32_e32 v117, v124, v117
	v_add_f32_e32 v116, v116, v117
	v_add_f32_e32 v116, v119, v116
	v_mul_f32_e32 v116, v123, v116
	v_add_f32_e32 v115, v115, v116
	v_add_f32_e32 v116, v126, v115
	v_mul_f32_e32 v118, v116, v116
	v_sub_f32_e32 v119, v116, v126
	v_fmamk_f32 v120, v118, 0x3e9b6dac, v160
	v_sub_f32_e32 v119, v115, v119
	v_mul_f32_e32 v115, v116, v118
	v_fmaak_f32 v147, v118, v120, 0x3f2aaada
	v_ldexp_f32 v121, v119, 1
	v_pk_mul_f32 v[118:119], v[114:115], v[146:147]
	v_ldexp_f32 v117, v116, 1
	v_fma_f32 v116, v114, s44, -v118
	v_fmac_f32_e32 v116, 0xb102e308, v114
	v_pk_add_f32 v[114:115], v[118:119], v[116:117]
	v_mov_b32_e32 v120, v118
	v_sub_f32_e32 v124, v115, v117
	v_pk_add_f32 v[122:123], v[114:115], v[118:119] neg_lo:[0,1] neg_hi:[0,1]
	v_sub_f32_e32 v118, v119, v124
	v_add_f32_e32 v121, v121, v118
	v_pk_add_f32 v[118:119], v[114:115], v[120:121]
	v_mov_b32_e32 v117, v114
	v_mov_b32_e32 v123, v119
	v_pk_add_f32 v[126:127], v[116:117], v[122:123] neg_lo:[0,1] neg_hi:[0,1]
	v_pk_add_f32 v[116:117], v[116:117], v[122:123]
	v_mov_b32_e32 v125, v114
	v_pk_add_f32 v[122:123], v[116:117], v[114:115] op_sel:[1,0] op_sel_hi:[0,1] neg_lo:[0,1] neg_hi:[0,1]
	v_mov_b32_e32 v124, v121
	v_mov_b32_e32 v120, v119
	v_mov_b32_e32 v121, v117
	v_pk_mov_b32 v[114:115], v[114:115], v[122:123] op_sel:[1,0]
	v_pk_add_f32 v[118:119], v[118:119], v[122:123] op_sel_hi:[1,0] neg_lo:[0,1] neg_hi:[0,1]
	v_pk_add_f32 v[114:115], v[120:121], v[114:115] neg_lo:[0,1] neg_hi:[0,1]
	v_mov_b32_e32 v118, v126
	v_pk_add_f32 v[114:115], v[124:125], v[114:115] neg_lo:[0,1] neg_hi:[0,1]
	v_mov_b32_e32 v127, v117
	v_pk_add_f32 v[118:119], v[118:119], v[114:115]
	s_nop 0
	v_pk_add_f32 v[120:121], v[118:119], v[118:119] op_sel:[0,1] op_sel_hi:[1,0]
	s_nop 0
	v_pk_add_f32 v[116:117], v[116:117], v[120:121] op_sel:[1,0] op_sel_hi:[0,1]
	v_mov_b32_e32 v119, v116
	v_mov_b32_e32 v115, v120
	v_pk_add_f32 v[120:121], v[118:119], v[126:127] neg_lo:[0,1] neg_hi:[0,1]
	v_add_u32_e32 v119, -16, v173
	v_sub_f32_e32 v117, v118, v120
	v_pk_add_f32 v[114:115], v[114:115], v[120:121] neg_lo:[0,1] neg_hi:[0,1]
	v_sub_f32_e32 v117, v126, v117
	v_add_f32_e32 v114, v114, v117
	v_add_f32_e32 v114, v114, v115
	v_add_f32_e32 v114, v116, v114
	v_cndmask_b32_e32 v114, v172, v114, vcc
	v_cmp_lt_f32_e64 vcc, |v133|, s45
	v_add_u32_e32 v116, -2, v173
	v_add_u32_e32 v117, -4, v173
	v_cndmask_b32_e32 v114, v114, v133, vcc
	v_sub_f32_e32 v114, v132, v114
	ds_bpermute_b32 v115, v130, v114
	v_cmp_lt_i32_e32 vcc, v116, v129
	v_cmp_lt_i32_e64 s[0:1], v117, v129
	v_add_u32_e32 v118, -8, v173
	v_cndmask_b32_e32 v116, v116, v173, vcc
	s_waitcnt lgkmcnt(0)
	v_add_f32_e32 v115, v114, v115
	v_cmp_eq_u32_e32 vcc, 0, v113
	v_lshlrev_b32_e32 v116, 2, v116
	v_cndmask_b32_e64 v117, v117, v173, s[0:1]
	v_cndmask_b32_e32 v114, v115, v114, vcc
	ds_bpermute_b32 v115, v116, v114
	v_cmp_gt_u32_e64 s[0:1], 2, v113
	v_lshlrev_b32_e32 v117, 2, v117
	v_cmp_lt_i32_e64 s[6:7], v118, v129
	v_cmp_lt_i32_e64 s[8:9], v119, v129
	s_waitcnt lgkmcnt(0)
	v_add_f32_e32 v115, v114, v115
	v_cndmask_b32_e64 v114, v115, v114, s[0:1]
	ds_bpermute_b32 v115, v117, v114
	v_cndmask_b32_e64 v118, v118, v173, s[6:7]
	v_cmp_gt_u32_e64 s[6:7], 4, v113
	v_lshlrev_b32_e32 v118, 2, v118
	v_cndmask_b32_e64 v119, v119, v173, s[8:9]
	s_waitcnt lgkmcnt(0)
	v_add_f32_e32 v115, v114, v115
	v_cndmask_b32_e64 v114, v115, v114, s[6:7]
	ds_bpermute_b32 v115, v118, v114
	v_cmp_gt_u32_e64 s[8:9], 8, v113
	v_lshlrev_b32_e32 v119, 2, v119
	v_subrev_u32_e32 v120, 32, v173
	v_cmp_lt_i32_e64 s[10:11], v120, v129
	s_waitcnt lgkmcnt(0)
	v_add_f32_e32 v115, v114, v115
	v_cndmask_b32_e64 v114, v115, v114, s[8:9]
	ds_bpermute_b32 v115, v119, v114
	v_cndmask_b32_e64 v120, v120, v173, s[10:11]
	v_cmp_gt_u32_e64 s[10:11], 16, v113
	v_lshlrev_b32_e32 v120, 2, v120
	s_waitcnt vmcnt(0)
	v_add_f32_e32 v121, v131, v128
	s_waitcnt lgkmcnt(0)
	v_add_f32_e32 v115, v114, v115
	v_cndmask_b32_e64 v114, v115, v114, s[10:11]
	ds_bpermute_b32 v115, v120, v114
	s_waitcnt lgkmcnt(0)
	v_add_f32_e32 v115, v114, v115
	v_cndmask_b32_e64 v114, v115, v114, s[12:13]
	v_sub_f32_e32 v115, v121, v114
	ds_bpermute_b32 v121, v130, v115
	s_waitcnt lgkmcnt(0)
	v_max_f32_e32 v121, v121, v121
	v_max_f32_e32 v121, v115, v121
	v_cndmask_b32_e32 v121, v121, v115, vcc
	ds_bpermute_b32 v116, v116, v121
	s_waitcnt lgkmcnt(0)
	v_max_f32_e32 v116, v116, v116
	v_max_f32_e32 v116, v121, v116
	v_cndmask_b32_e64 v116, v116, v121, s[0:1]
	ds_bpermute_b32 v117, v117, v116
	s_waitcnt lgkmcnt(0)
	v_max_f32_e32 v117, v117, v117
	v_max_f32_e32 v117, v116, v117
	v_cndmask_b32_e64 v117, v117, v116, s[6:7]
	ds_bpermute_b32 v118, v118, v117
	v_lshl_or_b32 v116, v152, 3, v181
	s_waitcnt lgkmcnt(0)
	v_max_f32_e32 v118, v118, v118
	v_max_f32_e32 v118, v117, v118
	v_cndmask_b32_e64 v118, v118, v117, s[8:9]
	ds_bpermute_b32 v119, v119, v118
	v_ashrrev_i32_e32 v117, 31, v116
	v_lshlrev_b64 v[116:117], 17, v[116:117]
	v_lshl_add_u64 v[116:117], s[18:19], 0, v[116:117]
	v_lshl_add_u64 v[116:117], v[116:117], 0, v[144:145]
	s_waitcnt lgkmcnt(0)
	v_max_f32_e32 v119, v119, v119
	v_max_f32_e32 v119, v118, v119
	v_cndmask_b32_e64 v121, v119, v118, s[10:11]
	ds_bpermute_b32 v120, v120, v121
	v_lshlrev_b32_e32 v144, 4, v113
	v_lshl_add_u64 v[118:119], v[116:117], 0, v[144:145]
	v_max_f32_e32 v113, v121, v121
	v_mov_b32_e32 v117, v145
	s_waitcnt lgkmcnt(0)
	v_max_f32_e32 v116, v120, v120
	v_max_f32_e32 v113, v113, v116
	v_cndmask_b32_e64 v116, v113, v121, s[12:13]
	global_store_dwordx4 v[118:119], v[114:117], off
	s_branch .LBB0_327
